# grid barrier tail rewritten by hand: XCD-last workgroup adds to TOP without return, all workgroups poll the TOP count (two fewer hops)
# baseline (speedup 1.0000x reference)
; __device__ __forceinline__ unsigned xb_ld(unsigned* p)              { return __hip_atomic_load(p, __ATOMIC_RELAXED, __HIP_MEMORY_SCOPE_AGENT); }
; __device__ __forceinline__ unsigned xb_add(unsigned* p, unsigned v) { return __hip_atomic_fetch_add(p, v, __ATOMIC_RELAXED, __HIP_MEMORY_SCOPE_AGENT); }
; #define XB_SPIN(cond, bar) do { unsigned _sp = 0; while (cond) { __builtin_amdgcn_s_sleep(1); \
;     if ((++_sp & 255u) == 0u) { if (xb_ld(&(bar)[XB_TMO])) break; if (_sp > XB_SPIN_CAP) { atomicAdd(&(bar)[XB_TMO], 1u); break; } } } } while (0)
; __device__ __forceinline__ void xcd_barrier(const XcdBarrier& b) {
;     ...
;     if (threadIdx.x == 0) {
;         unsigned* bar = b.bar;
;         __builtin_amdgcn_s_waitcnt(0);
;         unsigned nloc = b.st[0], nx = b.st[1];
;         if (nloc == 0u) { xcd_barrier_complete(bar, b.x, nloc, nx); b.st[0] = nloc; b.st[1] = nx; }
;         const unsigned old = xb_add(&bar[XB_XSUB(b.x)], 1u);
;         const unsigned gen = old / nloc;
;         if (old + 1u == (gen + 1u) * nloc) {
;             __builtin_amdgcn_fence(__ATOMIC_RELEASE, "agent");
;             asm volatile("s_waitcnt vmcnt(0)" ::: "memory");
;             const unsigned og = xb_add(&bar[XB_TOP], 1u);
;             const unsigned tg = og / nx;
;             if (og + 1u == (tg + 1u) * nx) xb_add(&bar[XB_TOPGEN], 1u);
;             else XB_SPIN(xb_ld(&bar[XB_TOPGEN]) == tg, bar);
;             __builtin_amdgcn_fence(__ATOMIC_ACQUIRE, "agent");
;             xb_add(&bar[XB_XGEN(b.x)], 1u);
;             asm volatile("s_waitcnt vmcnt(0)" ::: "memory");
;         } else {
;             XB_SPIN(xb_ld(&bar[XB_XGEN(b.x)]) == gen, bar);
;             __builtin_amdgcn_fence(__ATOMIC_ACQUIRE, "agent");
;             asm volatile("s_waitcnt vmcnt(0)" ::: "memory");
;         }
.LBB0_100:
	s_mov_b32 s2, 0x27ff0
	s_mov_b32 s3, 0x27ff4
	v_readlane_b32 s12, v254, 41
	v_readlane_b32 s13, v254, 42
	s_waitcnt lgkmcnt(0)
	v_mov_b32_e32 v0, s2
	v_mov_b32_e32 v4, s3
	ds_read_b32 v3, v0
	ds_read_b32 v2, v4
	v_mov_b32_e32 v5, 0
	v_mov_b32_e32 v6, 1
	s_nop 1
	global_atomic_add v6, v5, v6, s[12:13] sc0
	v_readlane_b32 s2, v254, 45
	v_readlane_b32 s3, v254, 46
	s_waitcnt vmcnt(0) lgkmcnt(0)
	v_cvt_f32_u32_e32 v0, v3
	v_sub_u32_e32 v4, 0, v3
	v_rcp_iflag_f32_e32 v0, v0
	s_nop 0
	v_mul_f32_e32 v0, 0x4f7ffffe, v0
	v_cvt_u32_f32_e32 v0, v0
	v_mul_lo_u32 v4, v4, v0
	v_mul_hi_u32 v4, v0, v4
	v_add_u32_e32 v0, v0, v4
	v_mul_hi_u32 v0, v6, v0
	v_mul_lo_u32 v4, v0, v3
	v_sub_u32_e32 v4, v6, v4
	v_add_u32_e32 v7, 1, v0
	v_cmp_ge_u32_e32 vcc, v4, v3
	s_nop 1
	v_cndmask_b32_e32 v0, v0, v7, vcc
	v_sub_u32_e32 v7, v4, v3
	v_cndmask_b32_e32 v4, v4, v7, vcc
	v_add_u32_e32 v7, 1, v0
	v_cmp_ge_u32_e32 vcc, v4, v3
	s_nop 1
	v_cndmask_b32_e32 v0, v0, v7, vcc
	v_add_u32_e32 v7, 1, v0
	v_mul_lo_u32 v4, v7, v3
	v_mul_lo_u32 v7, v7, v2
	v_add_u32_e32 v6, 1, v6
	v_cmp_ne_u32_e32 vcc, v6, v4
	s_mov_b32 s98, 0
	s_cbranch_vccnz .Lxb0_poll
	buffer_wbl2 sc1
	s_waitcnt vmcnt(0)
	v_mov_b32_e32 v6, 1
	global_atomic_add v5, v6, s[2:3]
.Lxb0_poll:
	global_load_dword v6, v5, s[2:3] sc1
	s_waitcnt vmcnt(0)
	v_cmp_lt_u32_e32 vcc, v6, v7
	s_cbranch_vccz .Lxb0_done
	s_sleep 1
	s_add_i32 s98, s98, 1
	s_cmp_lt_u32 s98, 0x40000
	s_cbranch_scc1 .Lxb0_poll
.Lxb0_done:
	buffer_inv sc1
	s_waitcnt vmcnt(0)

; __device__ __forceinline__ unsigned xb_ld(unsigned* p)              { return __hip_atomic_load(p, __ATOMIC_RELAXED, __HIP_MEMORY_SCOPE_AGENT); }
; __device__ __forceinline__ unsigned xb_add(unsigned* p, unsigned v) { return __hip_atomic_fetch_add(p, v, __ATOMIC_RELAXED, __HIP_MEMORY_SCOPE_AGENT); }
; #define XB_SPIN(cond, bar) do { unsigned _sp = 0; while (cond) { __builtin_amdgcn_s_sleep(1); \
;     if ((++_sp & 255u) == 0u) { if (xb_ld(&(bar)[XB_TMO])) break; if (_sp > XB_SPIN_CAP) { atomicAdd(&(bar)[XB_TMO], 1u); break; } } } } while (0)
; __device__ __forceinline__ void xcd_barrier(const XcdBarrier& b) {
;     ...
;     if (threadIdx.x == 0) {
;         unsigned* bar = b.bar;
;         __builtin_amdgcn_s_waitcnt(0);
;         unsigned nloc = b.st[0], nx = b.st[1];
;         if (nloc == 0u) { xcd_barrier_complete(bar, b.x, nloc, nx); b.st[0] = nloc; b.st[1] = nx; }
;         const unsigned old = xb_add(&bar[XB_XSUB(b.x)], 1u);
;         const unsigned gen = old / nloc;
;         if (old + 1u == (gen + 1u) * nloc) {
;             __builtin_amdgcn_fence(__ATOMIC_RELEASE, "agent");
;             asm volatile("s_waitcnt vmcnt(0)" ::: "memory");
;             const unsigned og = xb_add(&bar[XB_TOP], 1u);
;             const unsigned tg = og / nx;
;             if (og + 1u == (tg + 1u) * nx) xb_add(&bar[XB_TOPGEN], 1u);
;             else XB_SPIN(xb_ld(&bar[XB_TOPGEN]) == tg, bar);
;             __builtin_amdgcn_fence(__ATOMIC_ACQUIRE, "agent");
;             xb_add(&bar[XB_XGEN(b.x)], 1u);
;             asm volatile("s_waitcnt vmcnt(0)" ::: "memory");
;         } else {
;             XB_SPIN(xb_ld(&bar[XB_XGEN(b.x)]) == gen, bar);
;             __builtin_amdgcn_fence(__ATOMIC_ACQUIRE, "agent");
;             asm volatile("s_waitcnt vmcnt(0)" ::: "memory");
;         }
.LBB0_469:
	v_readlane_b32 s2, v254, 59
	v_readlane_b32 s3, v254, 60
	v_readlane_b32 s12, v254, 41
	v_readlane_b32 s13, v254, 42
	s_waitcnt lgkmcnt(0)
	v_mov_b32_e32 v0, s2
	v_mov_b32_e32 v4, s3
	ds_read_b32 v3, v0
	ds_read_b32 v2, v4
	v_mov_b32_e32 v5, 0
	v_mov_b32_e32 v6, 1
	s_nop 1
	global_atomic_add v6, v5, v6, s[12:13] sc0
	v_readlane_b32 s2, v254, 45
	v_readlane_b32 s3, v254, 46
	s_waitcnt vmcnt(0) lgkmcnt(0)
	v_cvt_f32_u32_e32 v0, v3
	v_sub_u32_e32 v4, 0, v3
	v_rcp_iflag_f32_e32 v0, v0
	s_nop 0
	v_mul_f32_e32 v0, 0x4f7ffffe, v0
	v_cvt_u32_f32_e32 v0, v0
	v_mul_lo_u32 v4, v4, v0
	v_mul_hi_u32 v4, v0, v4
	v_add_u32_e32 v0, v0, v4
	v_mul_hi_u32 v0, v6, v0
	v_mul_lo_u32 v4, v0, v3
	v_sub_u32_e32 v4, v6, v4
	v_add_u32_e32 v7, 1, v0
	v_cmp_ge_u32_e32 vcc, v4, v3
	s_nop 1
	v_cndmask_b32_e32 v0, v0, v7, vcc
	v_sub_u32_e32 v7, v4, v3
	v_cndmask_b32_e32 v4, v4, v7, vcc
	v_add_u32_e32 v7, 1, v0
	v_cmp_ge_u32_e32 vcc, v4, v3
	s_nop 1
	v_cndmask_b32_e32 v0, v0, v7, vcc
	v_add_u32_e32 v7, 1, v0
	v_mul_lo_u32 v4, v7, v3
	v_mul_lo_u32 v7, v7, v2
	v_add_u32_e32 v6, 1, v6
	v_cmp_ne_u32_e32 vcc, v6, v4
	s_mov_b32 s98, 0
	s_cbranch_vccnz .Lxb1_poll
	buffer_wbl2 sc1
	s_waitcnt vmcnt(0)
	v_mov_b32_e32 v6, 1
	global_atomic_add v5, v6, s[2:3]

; __device__ __forceinline__ unsigned xb_ld(unsigned* p)              { return __hip_atomic_load(p, __ATOMIC_RELAXED, __HIP_MEMORY_SCOPE_AGENT); }
; #define XB_SPIN(cond, bar) do { unsigned _sp = 0; while (cond) { __builtin_amdgcn_s_sleep(1); \
;     if ((++_sp & 255u) == 0u) { if (xb_ld(&(bar)[XB_TMO])) break; if (_sp > XB_SPIN_CAP) { atomicAdd(&(bar)[XB_TMO], 1u); break; } } } } while (0)
; __device__ __forceinline__ void xcd_barrier(const XcdBarrier& b) {
;     ...
;         } else {
;             XB_SPIN(xb_ld(&bar[XB_XGEN(b.x)]) == gen, bar);
;             __builtin_amdgcn_fence(__ATOMIC_ACQUIRE, "agent");
;             asm volatile("s_waitcnt vmcnt(0)" ::: "memory");
;         }
;     }
;     __syncthreads();
.Lxb10_done:
	buffer_inv sc1
	s_waitcnt vmcnt(0)
	s_mov_b64 s[12:13], exec
	s_getpc_b64 s[98:99]
